# stack + pass-prologue tile-1 loads issued with tile-0/Q loads + proj epilogue rstd loads hoisted
# baseline (speedup 1.0000x reference)
.LBB0_336:
	v_mov_b32_e32 v52, v162
	v_mov_b32_e32 v123, v99
	v_ashrrev_i32_e32 v50, 4, v52
	v_lshlrev_b32_e32 v20, 3, v52
	v_add_u32_e32 v21, 32, v50
	v_and_b32_e32 v24, 0x78, v20
	v_mad_i64_i32 v[2:3], s[12:13], v50, s52, 0
	v_mad_i64_i32 v[4:5], s[12:13], v21, s52, 0
	v_or_b32_e32 v2, v2, v24
	v_or_b32_e32 v4, v4, v24
	v_lshlrev_b64 v[10:11], 1, v[2:3]
	v_lshlrev_b64 v[12:13], 1, v[4:5]
	v_lshl_add_u64 v[2:3], s[36:37], 0, v[10:11]
	v_lshl_add_u64 v[6:7], s[36:37], 0, v[12:13]
	v_lshl_add_u64 v[10:11], s[34:35], 0, v[10:11]
	v_lshl_add_u64 v[14:15], s[34:35], 0, v[12:13]
	global_load_dwordx4 v[2:5], v[2:3], off
	s_nop 0
	global_load_dwordx4 v[6:9], v[6:7], off
	s_nop 0
	global_load_dwordx4 v[10:13], v[10:11], off
	s_nop 0
	global_load_dwordx4 v[14:17], v[14:15], off
	s_lshl_b32 s12, s8, 7
	s_add_u32 s8, s76, s12
	s_addc_u32 s9, s77, 0
	v_ashrrev_i32_e32 v26, 1, v52
	v_bfe_u32 v51, v52, 5, 1
	v_bfi_b32 v23, s18, v26, v52
	v_mov_b64_e32 v[18:19], s[8:9]
	v_bfe_u32 v27, v20, 5, 2
	v_lshlrev_b32_e32 v28, 5, v50
	v_and_b32_e32 v20, 24, v20
	v_add_u32_e32 v30, 64, v50
	v_lshrrev_b32_e32 v22, 5, v52
	v_lshlrev_b32_e32 v98, 4, v51
	v_add_u32_e32 v31, 0x60, v50
	v_mad_i64_i32 v[18:19], s[8:9], v23, s49, v[18:19]
	v_and_or_b32 v28, v28, s51, v20
	v_lshrrev_b32_e32 v33, 1, v21
	v_lshlrev_b32_e32 v35, 8, v21
	v_mad_i64_i32 v[20:21], s[8:9], v30, s52, 0
	v_and_or_b32 v32, v22, s50, v27
	v_mad_i64_i32 v[22:23], s[8:9], v31, s52, 0
	v_lshl_add_u64 v[18:19], v[18:19], 0, v[98:99]
	v_lshlrev_b32_e32 v28, 1, v28
	v_or_b32_e32 v20, v20, v24
	v_and_b32_e32 v25, 0x70, v52
	v_lshlrev_b32_e32 v29, 8, v50
	v_lshlrev_b32_e32 v34, 1, v24
	v_and_or_b32 v27, v33, s50, v27
	v_or_b32_e32 v22, v22, v24
	global_load_dwordx4 v[118:121], v[18:19], off
	global_load_dwordx4 v[114:117], v[18:19], off offset:32
	global_load_dwordx4 v[110:113], v[18:19], off offset:64
	global_load_dwordx4 v[106:109], v[18:19], off offset:96
	v_lshl_or_b32 v24, v32, 9, v28
	v_lshlrev_b64 v[18:19], 1, v[20:21]
	v_bitop3_b32 v29, v34, v29, v25 bitop3:0xde
	v_bitop3_b32 v25, v34, v35, v25 bitop3:0xde
	v_lshl_or_b32 v27, v27, 9, v28
	v_lshlrev_b64 v[20:21], 1, v[22:23]
	v_add_u32_e32 v183, 0, v24
	v_lshl_add_u64 v[22:23], s[36:37], 0, v[18:19]
	v_add_u32_e32 v181, 0, v29
	v_add_u32_e32 v182, 0, v25
	v_add_u32_e32 v184, 0, v27
	v_lshl_add_u64 v[24:25], s[36:37], 0, v[20:21]
	v_lshl_add_u64 v[18:19], s[34:35], 0, v[18:19]
	v_lshl_add_u64 v[20:21], s[34:35], 0, v[20:21]
	global_load_dwordx4 v[34:37], v[22:23], off
	global_load_dwordx4 v[38:41], v[24:25], off
	global_load_dwordx4 v[42:45], v[18:19], off
	global_load_dwordx4 v[46:49], v[20:21], off
	s_waitcnt vmcnt(0)
	v_and_b32_e32 v55, 63, v52
	v_and_b32_e32 v54, 0xffffffe0, v26
	v_and_b32_e32 v53, 31, v52
	v_add_u32_e32 v185, s75, v54
	v_cmp_gt_u32_e32 vcc, 32, v55
	v_or_b32_e32 v178, v185, v53
	v_mov_b32_e32 v124, v99
	v_cndmask_b32_e32 v122, 0, v170, vcc
	v_mov_b32_e32 v125, v99
	s_barrier
	s_waitcnt vmcnt(7)
	ds_write_b128 v183, v[2:5]
	s_waitcnt vmcnt(6)
	ds_write_b128 v184, v[6:9]
	s_waitcnt vmcnt(5)
	ds_write_b128 v181, v[10:13] offset:32768
	s_waitcnt vmcnt(4)
	ds_write_b128 v182, v[14:17] offset:32768
	s_waitcnt lgkmcnt(0)
	s_barrier
	ds_read_b32 v2, v173
	ds_read_b32 v3, v171
	s_waitcnt lgkmcnt(1)
	v_readfirstlane_b32 s43, v2
	s_waitcnt lgkmcnt(0)
	v_readfirstlane_b32 s42, v3
	v_lshlrev_b32_e32 v18, 4, v52
	v_mfma_f32_32x32x16_bf16 v[2:17], v[122:125], v[102:105], 0
	v_lshlrev_b32_e32 v64, 8, v53
	v_and_b32_e32 v65, 0x70, v18
	s_add_i32 s8, s12, 0
	v_bitop3_b32 v18, v98, v64, v65 bitop3:0xde
	v_add_u32_e32 v186, s8, v18
	ds_read_b128 v[56:59], v186 offset:32768
	ds_read_b128 v[60:63], v186 offset:40960
	v_lshlrev_b32_e32 v179, 2, v51
	s_waitcnt vmcnt(7) lgkmcnt(1)
	v_mfma_f32_32x32x16_bf16 v[18:33], v[56:59], v[118:121], v[2:17]
	v_or_b32_e32 v56, 32, v98
	v_bitop3_b32 v56, v56, v64, v65 bitop3:0xde
	v_add_u32_e32 v187, s8, v56
	s_waitcnt lgkmcnt(0)
	v_mfma_f32_32x32x16_bf16 v[2:17], v[60:63], v[118:121], v[2:17]
	ds_read_b128 v[56:59], v187 offset:32768
	ds_read_b128 v[60:63], v187 offset:40960
	s_waitcnt vmcnt(6) lgkmcnt(1)
	v_mfma_f32_32x32x16_bf16 v[18:33], v[56:59], v[114:117], v[18:33]
	v_or_b32_e32 v56, 64, v98
	v_bitop3_b32 v56, v56, v64, v65 bitop3:0xde
	v_add_u32_e32 v188, s8, v56
	s_waitcnt lgkmcnt(0)
	v_mfma_f32_32x32x16_bf16 v[2:17], v[60:63], v[114:117], v[2:17]
	ds_read_b128 v[56:59], v188 offset:32768
	ds_read_b128 v[60:63], v188 offset:40960
	s_waitcnt vmcnt(5) lgkmcnt(1)
	v_mfma_f32_32x32x16_bf16 v[18:33], v[56:59], v[110:113], v[18:33]
	v_or_b32_e32 v56, 0x60, v98
	v_bitop3_b32 v56, v56, v64, v65 bitop3:0xde
	v_add_u32_e32 v189, s8, v56
	s_waitcnt lgkmcnt(0)
	v_mfma_f32_32x32x16_bf16 v[2:17], v[60:63], v[110:113], v[2:17]
	ds_read_b128 v[56:59], v189 offset:32768
	ds_read_b128 v[60:63], v189 offset:40960
	s_waitcnt vmcnt(4) lgkmcnt(1)
	v_mfma_f32_32x32x16_bf16 v[18:33], v[56:59], v[106:109], v[18:33]
	v_add_u32_e32 v56, 0x9e, v185
	v_cmp_gt_u32_e64 s[8:9], s53, v56
	s_waitcnt lgkmcnt(0)
	v_mfma_f32_32x32x16_bf16 v[2:17], v[60:63], v[106:109], v[2:17]
	s_and_saveexec_b64 s[12:13], s[8:9]
	s_cbranch_execz .LBB0_338
	v_sub_u32_e32 v51, v179, v178
	v_lshl_add_u32 v51, v51, 2, s1
	ds_read2_b32 v[56:57], v51 offset0:240 offset1:241
	ds_read2_b32 v[58:59], v51 offset0:242 offset1:243
	ds_read2_b32 v[60:61], v51 offset0:248 offset1:249
	ds_read2_b32 v[62:63], v51 offset0:250 offset1:251
	ds_read2_b32 v[64:65], v51 offset0:224 offset1:225
	ds_read2_b32 v[66:67], v51 offset0:226 offset1:227
	ds_read2_b32 v[68:69], v51 offset0:232 offset1:233
	ds_read2_b32 v[70:71], v51 offset0:234 offset1:235
	s_waitcnt lgkmcnt(4)
	v_pk_add_f32 v[32:33], v[32:33], v[62:63]
	v_pk_add_f32 v[30:31], v[30:31], v[60:61]
	v_pk_add_f32 v[28:29], v[28:29], v[58:59]
	v_pk_add_f32 v[26:27], v[26:27], v[56:57]
	s_waitcnt lgkmcnt(0)
	v_pk_add_f32 v[24:25], v[24:25], v[70:71]
	v_pk_add_f32 v[22:23], v[22:23], v[68:69]
	v_pk_add_f32 v[20:21], v[20:21], v[66:67]
	v_pk_add_f32 v[18:19], v[18:19], v[64:65]
	v_add_u32_e32 v64, 0x400, v51
	v_add_u32_e32 v66, 0x408, v51
	v_add_u32_e32 v68, 0x420, v51
	v_add_u32_e32 v70, 0x428, v51
	v_add_u32_e32 v56, 0x440, v51
	v_add_u32_e32 v58, 0x448, v51
	v_add_u32_e32 v60, 0x460, v51
	v_add_u32_e32 v51, 0x468, v51
	ds_read2_b32 v[56:57], v56 offset1:1
	ds_read2_b32 v[58:59], v58 offset1:1
	ds_read2_b32 v[60:61], v60 offset1:1
	ds_read2_b32 v[62:63], v51 offset1:1
	ds_read2_b32 v[64:65], v64 offset1:1
	ds_read2_b32 v[66:67], v66 offset1:1
	ds_read2_b32 v[68:69], v68 offset1:1
	ds_read2_b32 v[70:71], v70 offset1:1
	s_waitcnt lgkmcnt(4)
	v_pk_add_f32 v[16:17], v[16:17], v[62:63]
	v_pk_add_f32 v[14:15], v[14:15], v[60:61]
	v_pk_add_f32 v[12:13], v[12:13], v[58:59]
	v_pk_add_f32 v[10:11], v[10:11], v[56:57]
	s_waitcnt lgkmcnt(0)
	v_pk_add_f32 v[8:9], v[8:9], v[70:71]
	v_pk_add_f32 v[6:7], v[6:7], v[68:69]
	v_pk_add_f32 v[4:5], v[4:5], v[66:67]
	v_pk_add_f32 v[2:3], v[2:3], v[64:65]
